# D5: query row's selected key indices staged once per row in a wave-private LDS strip (no dependent global load per group); groups whose largest key index is >= 128 tokens back use the constant far-dis
# speedup vs baseline: 1.1561x; 1.0065x over previous
; #define SA_GATHER(GR, SELV) do { _Pragma("unroll") for (int i = 0; i < 8; ++i) { \
;             unsigned sidx = ((SELV)[i >> 1] >> ((i & 1) * 16)) & 0xFFFFu; sidx = sidx == 0xFFFFu ? 0u : sidx; \
;             (GR)[i] = *(const u32x4*)(kg + (size_t)sidx * 128 + r * 8); } } while (0)
; __device__ __forceinline__ void dsa_attn_phase(const Params& p, int j, unsigned char* smem) {
;     ...
;     for (int row = blockIdx.x * 8 + wave; row < MTOK; row += gridDim.x * 8) {
;         const int b = row >> 11, t = row & 2047;
;         const int nvalid = t + 1 < 256 ? t + 1 : 256, ng = (nvalid + 31) >> 5;
;         const h16* kg = ckv + (size_t)(b * 2048) * 128;
;         const unsigned short* srow = sel + (size_t)row * 256;
;         h16x8 qf[4];
; #pragma unroll
;         for (int kk = 0; kk < 4; ++kk) qf[kk] = *(const h16x8*)(qabs + (size_t)row * 2048 + r * 128 + kk * 32 + q * 8);
;         f32x4 O[8];
; #pragma unroll
;         for (int dt = 0; dt < 8; ++dt) O[dt] = (f32x4){0.f, 0.f, 0.f, 0.f};
;         float mrun = NINF, lrun = 0.f;
;         u32x4 selA = *(const u32x4*)(srow + 8 * q), selB = selA;
;         u32x4 grA[8], grB[8];
;     ...
;         SA_GATHER(grA, selA);
;         if (ng > 1) { selB = *(const u32x4*)(srow + 32 + 8 * q); SA_GATHER(grB, selB); }
.LBB0_95:
	v_ashrrev_i32_e32 v129, 31, v128
	v_lshlrev_b64 v[72:73], 9, v[128:129]
	v_lshl_add_u64 v[74:75], v[134:135], 0, v[72:73]
	v_and_b32_e32 v240, 63, v226
	v_lshlrev_b32_e32 v240, 3, v240
	v_readfirstlane_b32 s14, v74
	v_readfirstlane_b32 s15, v75
	s_nop 4
	global_load_dwordx2 v[238:239], v240, s[14:15]
	v_and_b32_e32 v0, 0xfffff800, v128
	v_ashrrev_i32_e32 v1, 31, v0
	v_lshlrev_b64 v[46:47], 8, v[0:1]
	v_lshl_add_u64 v[144:145], v[132:133], 0, v[46:47]
	v_lshlrev_b64 v[142:143], 12, v[128:129]
	v_lshl_add_u64 v[44:45], v[130:131], 0, v[142:143]
	v_readfirstlane_b32 s12, v144
	v_readfirstlane_b32 s13, v145
	v_and_b32_e32 v192, 15, v226
	v_lshlrev_b32_e32 v192, 4, v192
	global_load_dwordx4 v[0:3], v[44:45], off
	global_load_dwordx4 v[4:7], v[44:45], off offset:64
	global_load_dwordx4 v[8:11], v[44:45], off offset:128
	v_and_b32_e32 v129, 0x7ff, v128
	s_waitcnt vmcnt(3)
	v_lshlrev_b32_e32 v240, 3, v226
	v_add_u32_e32 v240, 0x22100, v240
	ds_write_b64 v240, v[238:239]
	v_lshrrev_b32_e32 v238, 6, v226
	v_lshlrev_b32_e32 v238, 9, v238
	v_bfe_u32 v239, v226, 4, 2
	v_lshl_add_u32 v238, v239, 4, v238
	v_add_u32_e32 v238, 0x22100, v238
	s_waitcnt lgkmcnt(0)
	v_readfirstlane_b32 s17, v129
	ds_read_b32 v241, v148 offset:512
	s_sub_i32 s17, s17, 0x80
	ds_read_b128 v[120:123], v238
	s_waitcnt lgkmcnt(0)
	v_bfe_u32 v48, v120, 0, 11
	v_bfe_u32 v52, v120, 16, 11
	v_bfe_u32 v56, v121, 0, 11
	v_bfe_u32 v60, v121, 16, 11
	v_bfe_u32 v64, v122, 0, 11
	v_bfe_u32 v68, v122, 16, 11
	v_bfe_u32 v76, v123, 0, 11
	v_bfe_u32 v88, v123, 16, 11
	v_lshl_add_u32 v48, v48, 8, v192
	v_lshl_add_u32 v52, v52, 8, v192
	v_lshl_add_u32 v56, v56, 8, v192
	v_lshl_add_u32 v60, v60, 8, v192
	v_lshl_add_u32 v64, v64, 8, v192
	v_lshl_add_u32 v68, v68, 8, v192
	v_lshl_add_u32 v76, v76, 8, v192
	v_lshl_add_u32 v88, v88, 8, v192
	v_mov_b64_e32 v[116:117], v[120:121]
	v_mov_b64_e32 v[118:119], v[122:123]
	global_load_dwordx4 v[44:47], v[44:45], off offset:192
	global_load_dwordx4 v[48:51], v48, s[12:13]
	s_nop 0
	global_load_dwordx4 v[52:55], v52, s[12:13]
	s_nop 0
	global_load_dwordx4 v[56:59], v56, s[12:13]
	s_nop 0
	global_load_dwordx4 v[60:63], v60, s[12:13]
	s_nop 0
	global_load_dwordx4 v[64:67], v64, s[12:13]
	s_nop 0
	global_load_dwordx4 v[68:71], v68, s[12:13]
	s_nop 0
	global_load_dwordx4 v[76:79], v76, s[12:13]
	v_cmp_lt_u32_e32 vcc, 31, v129
	s_nop 0
	global_load_dwordx4 v[88:91], v88, s[12:13]
	s_and_saveexec_b64 s[4:5], vcc
	s_cbranch_execz .LBB0_97
	ds_read_b128 v[116:119], v238 offset:64
	s_waitcnt lgkmcnt(0)
	v_bfe_u32 v12, v116, 0, 11
	v_bfe_u32 v16, v116, 16, 11
	v_bfe_u32 v20, v117, 0, 11
	v_bfe_u32 v24, v117, 16, 11
	v_bfe_u32 v28, v118, 0, 11
	v_bfe_u32 v32, v118, 16, 11
	v_bfe_u32 v36, v119, 0, 11
	v_bfe_u32 v40, v119, 16, 11
	v_lshl_add_u32 v12, v12, 8, v192
	v_lshl_add_u32 v16, v16, 8, v192
	v_lshl_add_u32 v20, v20, 8, v192
	v_lshl_add_u32 v24, v24, 8, v192
	v_lshl_add_u32 v28, v28, 8, v192
	v_lshl_add_u32 v32, v32, 8, v192
	v_lshl_add_u32 v36, v36, 8, v192
	v_lshl_add_u32 v40, v40, 8, v192
	global_load_dwordx4 v[12:15], v12, s[12:13]
	s_nop 0
	global_load_dwordx4 v[16:19], v16, s[12:13]
	s_nop 0
	global_load_dwordx4 v[20:23], v20, s[12:13]
	s_nop 0
	global_load_dwordx4 v[24:27], v24, s[12:13]
	s_nop 0
	global_load_dwordx4 v[28:31], v28, s[12:13]
	s_nop 0
	global_load_dwordx4 v[32:35], v32, s[12:13]
	s_nop 0
	global_load_dwordx4 v[36:39], v36, s[12:13]
	s_nop 0
	global_load_dwordx4 v[40:43], v40, s[12:13]
.LBB0_97:
	s_or_b64 exec, exec, s[4:5]
	v_lshl_add_u64 v[146:147], v[136:137], 0, v[72:73]
	v_add_u32_e32 v238, 0x80, v238
	v_min_u32_e32 v72, 0xff, v129
	v_add_u32_e32 v72, 32, v72
	v_mov_b32_e32 v182, 0
	v_mov_b64_e32 v[112:113], v[120:121]
	v_lshrrev_b32_e32 v139, 5, v72
	v_mov_b32_e32 v183, 0xff800000
	s_mov_b32 s10, 3
	s_mov_b64 s[4:5], 0
	v_mov_b32_e32 v108, 0
	v_mov_b32_e32 v109, v182
	v_mov_b32_e32 v110, v182
	v_mov_b32_e32 v111, v182
	v_mov_b32_e32 v104, 0
	v_mov_b32_e32 v105, v182
	v_mov_b32_e32 v106, v182
	v_mov_b32_e32 v107, v182
	v_mov_b32_e32 v100, 0
	v_mov_b32_e32 v101, v182
	v_mov_b32_e32 v102, v182
	v_mov_b32_e32 v103, v182
	v_mov_b32_e32 v96, 0
	v_mov_b32_e32 v97, v182
	v_mov_b32_e32 v98, v182
	v_mov_b32_e32 v99, v182
	v_mov_b32_e32 v92, 0
	v_mov_b32_e32 v93, v182
	v_mov_b32_e32 v94, v182
	v_mov_b32_e32 v95, v182
	v_mov_b32_e32 v84, 0
	v_mov_b32_e32 v85, v182
	v_mov_b32_e32 v86, v182
	v_mov_b32_e32 v87, v182
	v_mov_b32_e32 v72, 0
	v_mov_b32_e32 v73, v182
	v_mov_b32_e32 v74, v182
	v_mov_b32_e32 v75, v182
	v_mov_b32_e32 v80, 0
	v_mov_b32_e32 v81, v182
	v_mov_b32_e32 v82, v182
	v_mov_b32_e32 v83, v182
	v_mov_b64_e32 v[114:115], v[122:123]
	s_branch .LBB0_100
.LBB0_98:
	s_or_b64 exec, exec, s[8:9]
	s_waitcnt lgkmcnt(0)
	v_readlane_b32 s16, v119, 48
	s_lshr_b32 s16, s16, 16
	s_cmp_gt_i32 s16, s17
	s_cbranch_scc1 .Ld5_slow_a
	ds_read_b128 v[124:127], v157 offset:8192
	ds_read_b128 v[182:185], v158 offset:8192
	v_cmp_ne_u32_sdwa vcc, v116, s59 src0_sel:WORD_0 src1_sel:DWORD
	s_mov_b32 s8, 0xff800000
	s_waitcnt lgkmcnt(1)
	v_mfma_f32_16x16x32_f16 v[124:127], v[124:127], v[0:3], 0
	ds_read_b128 v[186:189], v162 offset:8192
	s_waitcnt lgkmcnt(1)
	v_mfma_f32_16x16x32_f16 v[124:127], v[182:185], v[4:7], v[124:127]
	ds_read_b128 v[182:185], v159 offset:8192
	s_waitcnt lgkmcnt(0)
	v_mfma_f32_16x16x32_f16 v[124:127], v[182:185], v[8:11], v[124:127]
	ds_read_b128 v[182:185], v160 offset:8192
	s_waitcnt lgkmcnt(0)
	v_mfma_f32_16x16x32_f16 v[182:185], v[182:185], v[44:47], v[124:127]
	s_nop 4
	ds_read_b128 v[124:127], v161 offset:8192
	s_waitcnt lgkmcnt(0)
	v_mfma_f32_16x16x32_f16 v[124:127], v[124:127], v[0:3], 0
	v_mfma_f32_16x16x32_f16 v[124:127], v[186:189], v[4:7], v[124:127]
	ds_read_b128 v[186:189], v163 offset:8192
	s_waitcnt lgkmcnt(0)
	v_mfma_f32_16x16x32_f16 v[124:127], v[186:189], v[8:11], v[124:127]
	ds_read_b128 v[186:189], v164 offset:8192
	s_waitcnt lgkmcnt(0)
	v_mfma_f32_16x16x32_f16 v[124:127], v[186:189], v[44:47], v[124:127]
	ds_read_b64_tr_b16 v[204:205], v165 offset:8192
	ds_read_b64_tr_b16 v[206:207], v166 offset:8192
	ds_read_b64_tr_b16 v[208:209], v167 offset:8192
	ds_read_b64_tr_b16 v[210:211], v168 offset:8192
	ds_read_b64_tr_b16 v[212:213], v169 offset:8192
	ds_read_b64_tr_b16 v[214:215], v170 offset:8192
	ds_read_b64_tr_b16 v[216:217], v171 offset:8192
	ds_read_b64_tr_b16 v[218:219], v172 offset:8192
	ds_read_b64_tr_b16 v[220:221], v173 offset:8192
	ds_read_b64_tr_b16 v[222:223], v174 offset:8192
	s_nop 3
	v_add_f32_e32 v182, v182, v241
	s_nop 3
	v_cndmask_b32_e32 v182, v234, v182, vcc
	v_cmp_ne_u32_sdwa vcc, v116, s59 src0_sel:WORD_1 src1_sel:DWORD
	v_add_f32_e32 v183, v183, v241
	s_nop 3
	v_cndmask_b32_e32 v116, v234, v183, vcc
	v_cmp_ne_u32_sdwa vcc, v117, s59 src0_sel:WORD_0 src1_sel:DWORD
	v_max3_f32 v183, v182, s8, v116
	v_add_f32_e32 v184, v184, v241
	s_nop 3
	v_cndmask_b32_e32 v184, v234, v184, vcc
	v_cmp_ne_u32_sdwa vcc, v117, s59 src0_sel:WORD_1 src1_sel:DWORD
	v_add_f32_e32 v185, v185, v241
	v_cndmask_b32_e32 v117, v234, v185, vcc
	s_nop 3
	v_cmp_ne_u32_sdwa vcc, v118, s59 src0_sel:WORD_0 src1_sel:DWORD
	v_max3_f32 v183, v183, v184, v117
	v_add_f32_e32 v124, v124, v241
	s_nop 3
	v_cndmask_b32_e32 v124, v234, v124, vcc
	v_cmp_ne_u32_sdwa vcc, v118, s59 src0_sel:WORD_1 src1_sel:DWORD
	v_add_f32_e32 v125, v125, v241
	v_cndmask_b32_e32 v118, v234, v125, vcc
	v_max3_f32 v125, v183, v124, v118
	s_nop 3
	v_cmp_ne_u32_sdwa vcc, v119, s59 src0_sel:WORD_0 src1_sel:DWORD
	v_add_f32_e32 v126, v126, v241
	s_nop 3
	v_cndmask_b32_e32 v126, v234, v126, vcc
	v_cmp_ne_u32_sdwa vcc, v119, s59 src0_sel:WORD_1 src1_sel:DWORD
	v_add_f32_e32 v127, v127, v241
	v_cndmask_b32_e32 v119, v234, v127, vcc
	v_max3_f32 v125, v125, v126, v119
	v_mov_b32_e32 v127, v125
	s_nop 1
	v_permlane16_swap_b32_e32 v125, v127
	v_max_f32_e32 v127, v127, v127
	v_max_f32_e32 v125, v125, v125
	v_max_f32_e32 v125, v125, v127
	v_mov_b32_e32 v127, v125
	s_nop 1
	v_permlane32_swap_b32_e32 v125, v127
	v_max3_f32 v125, v181, v125, v127
	v_cmp_neq_f32_e32 vcc, s8, v125
	s_nop 1
	v_cndmask_b32_e32 v127, 0, v125, vcc
	v_sub_f32_e32 v116, v116, v127
	v_exp_f32_e32 v187, v116
	v_sub_f32_e32 v116, v184, v127
	v_exp_f32_e32 v188, v116
	v_sub_f32_e32 v116, v117, v127
	v_exp_f32_e32 v189, v116
	v_sub_f32_e32 v116, v124, v127
	v_exp_f32_e32 v190, v116
	v_sub_f32_e32 v116, v118, v127
	v_exp_f32_e32 v191, v116
	v_sub_f32_e32 v116, v126, v127
	v_sub_f32_e32 v181, v181, v127
	v_sub_f32_e32 v182, v182, v127
	v_exp_f32_e32 v126, v116
	v_sub_f32_e32 v116, v119, v127
	v_exp_f32_e32 v186, v182
	v_exp_f32_e32 v127, v116
	v_exp_f32_e32 v124, v181
	s_nop 1
	v_cvt_pk_f16_f32 v118, v190, v191
	v_cvt_pk_f16_f32 v119, v126, v127
	v_cvt_pk_f16_f32 v117, v188, v189
	v_cvt_pk_f16_f32 v116, v186, v187
	v_pk_mul_f32 v[110:111], v[110:111], v[124:125] op_sel_hi:[1,0]
	v_pk_mul_f32 v[108:109], v[108:109], v[124:125] op_sel_hi:[1,0]
	v_pk_mul_f32 v[106:107], v[106:107], v[124:125] op_sel_hi:[1,0]
	v_pk_mul_f32 v[104:105], v[104:105], v[124:125] op_sel_hi:[1,0]
	s_waitcnt lgkmcnt(8)
	v_mfma_f32_16x16x32_f16 v[108:111], v[204:207], v[116:119], v[108:111]
	s_nop 1
	v_pk_mul_f32 v[102:103], v[102:103], v[124:125] op_sel_hi:[1,0]
	v_pk_mul_f32 v[100:101], v[100:101], v[124:125] op_sel_hi:[1,0]
	s_waitcnt lgkmcnt(6)
	v_mfma_f32_16x16x32_f16 v[104:107], v[208:211], v[116:119], v[104:107]
	s_nop 1
	v_pk_mul_f32 v[98:99], v[98:99], v[124:125] op_sel_hi:[1,0]
	v_pk_mul_f32 v[96:97], v[96:97], v[124:125] op_sel_hi:[1,0]
	s_waitcnt lgkmcnt(4)
	v_mfma_f32_16x16x32_f16 v[100:103], v[212:215], v[116:119], v[100:103]
	s_nop 1
	v_pk_mul_f32 v[94:95], v[94:95], v[124:125] op_sel_hi:[1,0]
	v_pk_mul_f32 v[92:93], v[92:93], v[124:125] op_sel_hi:[1,0]
	s_waitcnt lgkmcnt(2)
	v_mfma_f32_16x16x32_f16 v[96:99], v[216:219], v[116:119], v[96:99]
	s_nop 1
	v_pk_mul_f32 v[86:87], v[86:87], v[124:125] op_sel_hi:[1,0]
	v_pk_mul_f32 v[84:85], v[84:85], v[124:125] op_sel_hi:[1,0]
	s_waitcnt lgkmcnt(0)
	v_mfma_f32_16x16x32_f16 v[92:95], v[220:223], v[116:119], v[92:95]
	ds_read_b64_tr_b16 v[182:183], v175 offset:8192
	ds_read_b64_tr_b16 v[184:185], v176 offset:8192
	v_pk_mul_f32 v[74:75], v[74:75], v[124:125] op_sel_hi:[1,0]
	v_pk_mul_f32 v[72:73], v[72:73], v[124:125] op_sel_hi:[1,0]
	s_waitcnt lgkmcnt(0)
	v_mfma_f32_16x16x32_f16 v[84:87], v[182:185], v[116:119], v[84:87]
	ds_read_b64_tr_b16 v[182:183], v177 offset:8192
	ds_read_b64_tr_b16 v[184:185], v178 offset:8192
	v_pk_mul_f32 v[82:83], v[82:83], v[124:125] op_sel_hi:[1,0]
	v_pk_mul_f32 v[80:81], v[80:81], v[124:125] op_sel_hi:[1,0]
	s_waitcnt lgkmcnt(0)
	v_mfma_f32_16x16x32_f16 v[72:75], v[182:185], v[116:119], v[72:75]
	ds_read_b64_tr_b16 v[182:183], v179 offset:8192
	ds_read_b64_tr_b16 v[184:185], v180 offset:8192
	v_mov_b32_e32 v181, v125
	s_waitcnt lgkmcnt(0)
	v_mfma_f32_16x16x32_f16 v[80:83], v[182:185], v[116:119], v[80:83]
	v_add_f32_e32 v116, 0, v186
	v_add_f32_e32 v116, v187, v116
	v_add_f32_e32 v116, v188, v116
	v_add_f32_e32 v116, v189, v116
	v_add_f32_e32 v116, v190, v116
	v_add_f32_e32 v116, v191, v116
	v_add_f32_e32 v116, v126, v116
	v_add_f32_e32 v116, v127, v116
	v_fmac_f32_e32 v116, v141, v124
	v_mov_b32_e32 v141, v116
	v_mov_b64_e32 v[116:117], v[120:121]
	v_mov_b64_e32 v[118:119], v[122:123]
	s_branch .LBB0_99
.Ld5_slow_a:
	v_sub_u32_sdwa v224, v129, v116 dst_sel:DWORD dst_unused:UNUSED_PAD src0_sel:DWORD src1_sel:WORD_0
	v_med3_i32 v224, v224, 0, v233
	v_lshl_add_u32 v224, v224, 2, v148
	ds_read_b32 v224, v224
	v_sub_u32_sdwa v225, v129, v116 dst_sel:DWORD dst_unused:UNUSED_PAD src0_sel:DWORD src1_sel:WORD_1
	v_med3_i32 v225, v225, 0, v233
	v_lshl_add_u32 v225, v225, 2, v148
	ds_read_b32 v225, v225
	v_sub_u32_sdwa v246, v129, v117 dst_sel:DWORD dst_unused:UNUSED_PAD src0_sel:DWORD src1_sel:WORD_0
	v_med3_i32 v246, v246, 0, v233
	v_lshl_add_u32 v246, v246, 2, v148
	ds_read_b32 v246, v246
	v_sub_u32_sdwa v247, v129, v117 dst_sel:DWORD dst_unused:UNUSED_PAD src0_sel:DWORD src1_sel:WORD_1
	v_med3_i32 v247, v247, 0, v233
	v_lshl_add_u32 v247, v247, 2, v148
	ds_read_b32 v247, v247
	v_sub_u32_sdwa v193, v129, v118 dst_sel:DWORD dst_unused:UNUSED_PAD src0_sel:DWORD src1_sel:WORD_0
	v_med3_i32 v193, v193, 0, v233
	v_lshl_add_u32 v193, v193, 2, v148
	ds_read_b32 v193, v193
	v_sub_u32_sdwa v194, v129, v118 dst_sel:DWORD dst_unused:UNUSED_PAD src0_sel:DWORD src1_sel:WORD_1
	v_med3_i32 v194, v194, 0, v233
	v_lshl_add_u32 v194, v194, 2, v148
	ds_read_b32 v194, v194
	v_sub_u32_sdwa v195, v129, v119 dst_sel:DWORD dst_unused:UNUSED_PAD src0_sel:DWORD src1_sel:WORD_0
	v_med3_i32 v195, v195, 0, v233
	v_lshl_add_u32 v195, v195, 2, v148
	ds_read_b32 v195, v195
	v_sub_u32_sdwa v248, v129, v119 dst_sel:DWORD dst_unused:UNUSED_PAD src0_sel:DWORD src1_sel:WORD_1
	v_med3_i32 v248, v248, 0, v233
	v_lshl_add_u32 v248, v248, 2, v148
	ds_read_b32 v248, v248
	ds_read_b128 v[124:127], v157 offset:8192
	ds_read_b128 v[182:185], v158 offset:8192
	v_cmp_ne_u32_sdwa vcc, v116, s59 src0_sel:WORD_0 src1_sel:DWORD
	s_mov_b32 s8, 0xff800000
	s_waitcnt lgkmcnt(1)
	v_mfma_f32_16x16x32_f16 v[124:127], v[124:127], v[0:3], 0
	ds_read_b128 v[186:189], v162 offset:8192
	s_waitcnt lgkmcnt(1)
	v_mfma_f32_16x16x32_f16 v[124:127], v[182:185], v[4:7], v[124:127]
	ds_read_b128 v[182:185], v159 offset:8192
	s_waitcnt lgkmcnt(0)
	v_mfma_f32_16x16x32_f16 v[124:127], v[182:185], v[8:11], v[124:127]
	ds_read_b128 v[182:185], v160 offset:8192
	s_waitcnt lgkmcnt(0)
	v_mfma_f32_16x16x32_f16 v[182:185], v[182:185], v[44:47], v[124:127]
	s_nop 4
	ds_read_b128 v[124:127], v161 offset:8192
	s_waitcnt lgkmcnt(0)
	v_mfma_f32_16x16x32_f16 v[124:127], v[124:127], v[0:3], 0
	v_mfma_f32_16x16x32_f16 v[124:127], v[186:189], v[4:7], v[124:127]
	ds_read_b128 v[186:189], v163 offset:8192
	s_waitcnt lgkmcnt(0)
	v_mfma_f32_16x16x32_f16 v[124:127], v[186:189], v[8:11], v[124:127]
	ds_read_b128 v[186:189], v164 offset:8192
	s_waitcnt lgkmcnt(0)
	v_mfma_f32_16x16x32_f16 v[124:127], v[186:189], v[44:47], v[124:127]
	ds_read_b64_tr_b16 v[204:205], v165 offset:8192
	ds_read_b64_tr_b16 v[206:207], v166 offset:8192
	ds_read_b64_tr_b16 v[208:209], v167 offset:8192
	ds_read_b64_tr_b16 v[210:211], v168 offset:8192
	ds_read_b64_tr_b16 v[212:213], v169 offset:8192
	ds_read_b64_tr_b16 v[214:215], v170 offset:8192
	ds_read_b64_tr_b16 v[216:217], v171 offset:8192
	ds_read_b64_tr_b16 v[218:219], v172 offset:8192
	ds_read_b64_tr_b16 v[220:221], v173 offset:8192
	ds_read_b64_tr_b16 v[222:223], v174 offset:8192
	s_nop 3
	v_add_f32_e32 v182, v182, v224
	s_nop 3
	v_cndmask_b32_e32 v182, v234, v182, vcc
	v_cmp_ne_u32_sdwa vcc, v116, s59 src0_sel:WORD_1 src1_sel:DWORD
	v_add_f32_e32 v183, v183, v225
	s_nop 3
	v_cndmask_b32_e32 v116, v234, v183, vcc
	v_cmp_ne_u32_sdwa vcc, v117, s59 src0_sel:WORD_0 src1_sel:DWORD
	v_max3_f32 v183, v182, s8, v116
	v_add_f32_e32 v184, v184, v246
	s_nop 3
	v_cndmask_b32_e32 v184, v234, v184, vcc
	v_cmp_ne_u32_sdwa vcc, v117, s59 src0_sel:WORD_1 src1_sel:DWORD
	v_add_f32_e32 v185, v185, v247
	v_cndmask_b32_e32 v117, v234, v185, vcc
	s_nop 3
	v_cmp_ne_u32_sdwa vcc, v118, s59 src0_sel:WORD_0 src1_sel:DWORD
	v_max3_f32 v183, v183, v184, v117
	v_add_f32_e32 v124, v124, v193
	s_nop 3
	v_cndmask_b32_e32 v124, v234, v124, vcc
	v_cmp_ne_u32_sdwa vcc, v118, s59 src0_sel:WORD_1 src1_sel:DWORD
	v_add_f32_e32 v125, v125, v194
	v_cndmask_b32_e32 v118, v234, v125, vcc
	v_max3_f32 v125, v183, v124, v118
	s_nop 3
	v_cmp_ne_u32_sdwa vcc, v119, s59 src0_sel:WORD_0 src1_sel:DWORD
	v_add_f32_e32 v126, v126, v195
	s_nop 3
	v_cndmask_b32_e32 v126, v234, v126, vcc
	v_cmp_ne_u32_sdwa vcc, v119, s59 src0_sel:WORD_1 src1_sel:DWORD
	v_add_f32_e32 v127, v127, v248
	v_cndmask_b32_e32 v119, v234, v127, vcc
	v_max3_f32 v125, v125, v126, v119
	v_mov_b32_e32 v127, v125
	s_nop 1
	v_permlane16_swap_b32_e32 v125, v127
	v_max_f32_e32 v127, v127, v127
	v_max_f32_e32 v125, v125, v125
	v_max_f32_e32 v125, v125, v127
	v_mov_b32_e32 v127, v125
	s_nop 1
	v_permlane32_swap_b32_e32 v125, v127
	v_max3_f32 v125, v181, v125, v127
	v_cmp_neq_f32_e32 vcc, s8, v125
	s_nop 1
	v_cndmask_b32_e32 v127, 0, v125, vcc
	v_sub_f32_e32 v116, v116, v127
	v_exp_f32_e32 v187, v116
	v_sub_f32_e32 v116, v184, v127
	v_exp_f32_e32 v188, v116
	v_sub_f32_e32 v116, v117, v127
	v_exp_f32_e32 v189, v116
	v_sub_f32_e32 v116, v124, v127
	v_exp_f32_e32 v190, v116
	v_sub_f32_e32 v116, v118, v127
	v_exp_f32_e32 v191, v116
	v_sub_f32_e32 v116, v126, v127
	v_sub_f32_e32 v181, v181, v127
	v_sub_f32_e32 v182, v182, v127
	v_exp_f32_e32 v126, v116
	v_sub_f32_e32 v116, v119, v127
	v_exp_f32_e32 v186, v182
	v_exp_f32_e32 v127, v116
	v_exp_f32_e32 v124, v181
	s_nop 1
	v_cvt_pk_f16_f32 v118, v190, v191
	v_cvt_pk_f16_f32 v119, v126, v127
	v_cvt_pk_f16_f32 v117, v188, v189
	v_cvt_pk_f16_f32 v116, v186, v187
	v_pk_mul_f32 v[110:111], v[110:111], v[124:125] op_sel_hi:[1,0]
	v_pk_mul_f32 v[108:109], v[108:109], v[124:125] op_sel_hi:[1,0]
	v_pk_mul_f32 v[106:107], v[106:107], v[124:125] op_sel_hi:[1,0]
	v_pk_mul_f32 v[104:105], v[104:105], v[124:125] op_sel_hi:[1,0]
	s_waitcnt lgkmcnt(8)
; #define SA_GATHER(GR, SELV) do { _Pragma("unroll") for (int i = 0; i < 8; ++i) { \
;             unsigned sidx = ((SELV)[i >> 1] >> ((i & 1) * 16)) & 0xFFFFu; sidx = sidx == 0xFFFFu ? 0u : sidx; \
;             (GR)[i] = *(const u32x4*)(kg + (size_t)sidx * 128 + r * 8); } } while (0)
; __device__ __forceinline__ void dsa_attn_phase(const Params& p, int j, unsigned char* smem) {
;     ...
;         SA_GATHER(grA, selA);
;         if (ng > 1) { selB = *(const u32x4*)(srow + 32 + 8 * q); SA_GATHER(grB, selB); }
;         for (int g = 0; g < ng; g += 2) {
;             SA_GROUP(grA, selA, g);
;             if (g + 1 < ng) SA_GROUP(grB, selB, g + 1);
;         }
	v_mfma_f32_16x16x32_f16 v[108:111], v[204:207], v[116:119], v[108:111]
	s_nop 1
	v_pk_mul_f32 v[102:103], v[102:103], v[124:125] op_sel_hi:[1,0]
	v_pk_mul_f32 v[100:101], v[100:101], v[124:125] op_sel_hi:[1,0]
	s_waitcnt lgkmcnt(6)
	v_mfma_f32_16x16x32_f16 v[104:107], v[208:211], v[116:119], v[104:107]
	s_nop 1
	v_pk_mul_f32 v[98:99], v[98:99], v[124:125] op_sel_hi:[1,0]
	v_pk_mul_f32 v[96:97], v[96:97], v[124:125] op_sel_hi:[1,0]
	s_waitcnt lgkmcnt(4)
	v_mfma_f32_16x16x32_f16 v[100:103], v[212:215], v[116:119], v[100:103]
	s_nop 1
	v_pk_mul_f32 v[94:95], v[94:95], v[124:125] op_sel_hi:[1,0]
	v_pk_mul_f32 v[92:93], v[92:93], v[124:125] op_sel_hi:[1,0]
	s_waitcnt lgkmcnt(2)
	v_mfma_f32_16x16x32_f16 v[96:99], v[216:219], v[116:119], v[96:99]
	s_nop 1
	v_pk_mul_f32 v[86:87], v[86:87], v[124:125] op_sel_hi:[1,0]
	v_pk_mul_f32 v[84:85], v[84:85], v[124:125] op_sel_hi:[1,0]
	s_waitcnt lgkmcnt(0)
	v_mfma_f32_16x16x32_f16 v[92:95], v[220:223], v[116:119], v[92:95]
	ds_read_b64_tr_b16 v[182:183], v175 offset:8192
	ds_read_b64_tr_b16 v[184:185], v176 offset:8192
	v_pk_mul_f32 v[74:75], v[74:75], v[124:125] op_sel_hi:[1,0]
	v_pk_mul_f32 v[72:73], v[72:73], v[124:125] op_sel_hi:[1,0]
	s_waitcnt lgkmcnt(0)
	v_mfma_f32_16x16x32_f16 v[84:87], v[182:185], v[116:119], v[84:87]
	ds_read_b64_tr_b16 v[182:183], v177 offset:8192
	ds_read_b64_tr_b16 v[184:185], v178 offset:8192
	v_pk_mul_f32 v[82:83], v[82:83], v[124:125] op_sel_hi:[1,0]
	v_pk_mul_f32 v[80:81], v[80:81], v[124:125] op_sel_hi:[1,0]
	s_waitcnt lgkmcnt(0)
	v_mfma_f32_16x16x32_f16 v[72:75], v[182:185], v[116:119], v[72:75]
	ds_read_b64_tr_b16 v[182:183], v179 offset:8192
	ds_read_b64_tr_b16 v[184:185], v180 offset:8192
	v_mov_b32_e32 v181, v125
	s_waitcnt lgkmcnt(0)
	v_mfma_f32_16x16x32_f16 v[80:83], v[182:185], v[116:119], v[80:83]
	v_add_f32_e32 v116, 0, v186
	v_add_f32_e32 v116, v187, v116
	v_add_f32_e32 v116, v188, v116
	v_add_f32_e32 v116, v189, v116
	v_add_f32_e32 v116, v190, v116
	v_add_f32_e32 v116, v191, v116
	v_add_f32_e32 v116, v126, v116
	v_add_f32_e32 v116, v127, v116
	v_fmac_f32_e32 v116, v141, v124
	v_mov_b32_e32 v141, v116
	v_mov_b64_e32 v[116:117], v[120:121]
	v_mov_b64_e32 v[118:119], v[122:123]
.LBB0_99:
	s_or_b64 exec, exec, s[6:7]
	s_add_i32 s10, s10, 2
	v_cmp_ge_u32_e32 vcc, s11, v139
	v_mov_b64_e32 v[122:123], v[114:115]
	v_lshl_add_u64 v[146:147], v[146:147], 0, s[80:81]
	v_add_u32_e32 v238, 0x80, v238
	s_or_b64 s[4:5], vcc, s[4:5]
	v_mov_b32_e32 v183, v181
	v_mov_b32_e32 v182, v141
	v_mov_b64_e32 v[120:121], v[112:113]
	s_andn2_b64 exec, exec, s[4:5]
	s_cbranch_execz .LBB0_94
.LBB0_100:
	s_add_i32 s11, s10, -1
	v_cmp_lt_u32_e32 vcc, s11, v139
	s_waitcnt vmcnt(7)
	ds_write_b128 v149, v[48:51]
	s_waitcnt vmcnt(6)
	ds_write_b128 v150, v[52:55] offset:256
	s_waitcnt vmcnt(5)
	ds_write_b128 v151, v[56:59] offset:512
	s_waitcnt vmcnt(4)
	ds_write_b128 v152, v[60:63] offset:768
	s_waitcnt vmcnt(3)
	ds_write_b128 v153, v[64:67]
	s_waitcnt vmcnt(2)
	ds_write_b128 v154, v[68:71]
	s_waitcnt vmcnt(1)
	ds_write_b128 v155, v[76:79]
	s_waitcnt vmcnt(0)
	ds_write_b128 v156, v[88:91]
	s_and_saveexec_b64 s[6:7], vcc
	s_cbranch_execz .LBB0_102
	ds_read_b128 v[112:115], v238
	s_waitcnt lgkmcnt(0)
	v_bfe_u32 v48, v112, 0, 11
	v_bfe_u32 v52, v112, 16, 11
	v_bfe_u32 v56, v113, 0, 11
	v_bfe_u32 v60, v113, 16, 11
	v_bfe_u32 v64, v114, 0, 11
	v_bfe_u32 v68, v114, 16, 11
	v_bfe_u32 v76, v115, 0, 11
	v_bfe_u32 v88, v115, 16, 11
	v_lshl_add_u32 v48, v48, 8, v192
	v_lshl_add_u32 v52, v52, 8, v192
	v_lshl_add_u32 v56, v56, 8, v192
	v_lshl_add_u32 v60, v60, 8, v192
	v_lshl_add_u32 v64, v64, 8, v192
	v_lshl_add_u32 v68, v68, 8, v192
	v_lshl_add_u32 v76, v76, 8, v192
	v_lshl_add_u32 v88, v88, 8, v192
	global_load_dwordx4 v[48:51], v48, s[12:13]
	s_nop 0
	global_load_dwordx4 v[52:55], v52, s[12:13]
	s_nop 0
	global_load_dwordx4 v[56:59], v56, s[12:13]
	s_nop 0
	global_load_dwordx4 v[60:63], v60, s[12:13]
	s_nop 0
	global_load_dwordx4 v[64:67], v64, s[12:13]
	s_nop 0
	global_load_dwordx4 v[68:71], v68, s[12:13]
	s_nop 0
	global_load_dwordx4 v[76:79], v76, s[12:13]
	s_nop 0
	global_load_dwordx4 v[88:91], v88, s[12:13]
.LBB0_102:
	s_or_b64 exec, exec, s[6:7]
	s_waitcnt lgkmcnt(0)
	v_readlane_b32 s16, v123, 48
	s_lshr_b32 s16, s16, 16
	s_cmp_gt_i32 s16, s17
	s_cbranch_scc1 .Ld5_slow_b
; #define SA_GATHER(GR, SELV) do { _Pragma("unroll") for (int i = 0; i < 8; ++i) { \
;             unsigned sidx = ((SELV)[i >> 1] >> ((i & 1) * 16)) & 0xFFFFu; sidx = sidx == 0xFFFFu ? 0u : sidx; \
;             (GR)[i] = *(const u32x4*)(kg + (size_t)sidx * 128 + r * 8); } } while (0)
; __device__ __forceinline__ void dsa_attn_phase(const Params& p, int j, unsigned char* smem) {
;     ...
;         SA_GATHER(grA, selA);
;         if (ng > 1) { selB = *(const u32x4*)(srow + 32 + 8 * q); SA_GATHER(grB, selB); }
;         for (int g = 0; g < ng; g += 2) {
;             SA_GROUP(grA, selA, g);
;             if (g + 1 < ng) SA_GROUP(grB, selB, g + 1);
	ds_read_b128 v[124:127], v157
	ds_read_b128 v[184:187], v158
	ds_read_b128 v[188:191], v162
	s_nop 5
	s_waitcnt lgkmcnt(2)
	v_mfma_f32_16x16x32_f16 v[124:127], v[124:127], v[0:3], 0
	s_nop 0
	v_cmp_ne_u32_sdwa vcc, v120, s59 src0_sel:WORD_0 src1_sel:DWORD
	s_mov_b32 s6, 0xff800000
	s_waitcnt lgkmcnt(1)
	v_mfma_f32_16x16x32_f16 v[124:127], v[184:187], v[4:7], v[124:127]
	ds_read_b128 v[184:187], v159
	s_nop 0
	s_waitcnt lgkmcnt(0)
	v_mfma_f32_16x16x32_f16 v[124:127], v[184:187], v[8:11], v[124:127]
	ds_read_b128 v[184:187], v160
	s_waitcnt lgkmcnt(0)
	v_mfma_f32_16x16x32_f16 v[184:187], v[184:187], v[44:47], v[124:127]
	s_nop 4
	ds_read_b128 v[124:127], v161
	s_nop 1
	v_add_f32_e32 v141, v184, v241
	s_nop 3
	s_waitcnt lgkmcnt(0)
	v_mfma_f32_16x16x32_f16 v[124:127], v[124:127], v[0:3], 0
	v_add_f32_e32 v181, v185, v241
	s_nop 1
	v_mfma_f32_16x16x32_f16 v[124:127], v[188:191], v[4:7], v[124:127]
	ds_read_b128 v[188:191], v163
	s_nop 1
	v_cndmask_b32_e32 v141, v234, v141, vcc
	v_cmp_ne_u32_sdwa vcc, v120, s59 src0_sel:WORD_1 src1_sel:DWORD
	s_waitcnt lgkmcnt(0)
	v_mfma_f32_16x16x32_f16 v[124:127], v[188:191], v[8:11], v[124:127]
	ds_read_b128 v[188:191], v164
	v_cndmask_b32_e32 v120, v234, v181, vcc
	v_add_f32_e32 v184, v186, v241
	v_cmp_ne_u32_sdwa vcc, v121, s59 src0_sel:WORD_0 src1_sel:DWORD
	v_add_f32_e32 v185, v187, v241
	v_max3_f32 v181, v141, s6, v120
	v_cndmask_b32_e32 v184, v234, v184, vcc
	v_cmp_ne_u32_sdwa vcc, v121, s59 src0_sel:WORD_1 src1_sel:DWORD
	s_nop 1
	v_cndmask_b32_e32 v121, v234, v185, vcc
	s_nop 3
	s_waitcnt lgkmcnt(0)
	v_mfma_f32_16x16x32_f16 v[124:127], v[188:191], v[44:47], v[124:127]
	ds_read_b64_tr_b16 v[204:205], v165
	ds_read_b64_tr_b16 v[206:207], v166
	ds_read_b64_tr_b16 v[208:209], v167
	ds_read_b64_tr_b16 v[210:211], v168
	ds_read_b64_tr_b16 v[212:213], v169
	ds_read_b64_tr_b16 v[214:215], v170
	ds_read_b64_tr_b16 v[216:217], v171
	ds_read_b64_tr_b16 v[218:219], v172
	ds_read_b64_tr_b16 v[220:221], v173
	ds_read_b64_tr_b16 v[222:223], v174
	v_cmp_ne_u32_sdwa vcc, v122, s59 src0_sel:WORD_0 src1_sel:DWORD
	v_max3_f32 v181, v181, v184, v121
	s_nop 4
	v_add_f32_e32 v124, v124, v241
	s_nop 3
	v_cndmask_b32_e32 v124, v234, v124, vcc
	v_cmp_ne_u32_sdwa vcc, v122, s59 src0_sel:WORD_1 src1_sel:DWORD
	v_add_f32_e32 v125, v125, v241
	v_cndmask_b32_e32 v122, v234, v125, vcc
	v_max3_f32 v125, v181, v124, v122
	s_nop 3
	v_cmp_ne_u32_sdwa vcc, v123, s59 src0_sel:WORD_0 src1_sel:DWORD
	v_add_f32_e32 v126, v126, v241
	s_nop 3
	v_cndmask_b32_e32 v126, v234, v126, vcc
	v_cmp_ne_u32_sdwa vcc, v123, s59 src0_sel:WORD_1 src1_sel:DWORD
	v_add_f32_e32 v127, v127, v241
	v_cndmask_b32_e32 v123, v234, v127, vcc
	v_max3_f32 v125, v125, v126, v123
	v_mov_b32_e32 v127, v125
	s_nop 1
	v_permlane16_swap_b32_e32 v125, v127
	v_max_f32_e32 v127, v127, v127
	v_max_f32_e32 v125, v125, v125
	v_max_f32_e32 v125, v125, v127
	v_mov_b32_e32 v127, v125
	s_nop 1
	v_permlane32_swap_b32_e32 v125, v127
	v_max3_f32 v181, v183, v125, v127
	v_cmp_neq_f32_e32 vcc, s6, v181
	s_add_i32 s6, s10, -2
	s_nop 0
	v_cndmask_b32_e32 v125, 0, v181, vcc
	v_sub_f32_e32 v120, v120, v125
	v_sub_f32_e32 v127, v183, v125
	v_exp_f32_e32 v183, v120
	v_sub_f32_e32 v120, v184, v125
	v_exp_f32_e32 v188, v120
	v_sub_f32_e32 v120, v121, v125
	v_exp_f32_e32 v189, v120
	v_sub_f32_e32 v120, v124, v125
	v_exp_f32_e32 v190, v120
	v_sub_f32_e32 v120, v122, v125
	v_exp_f32_e32 v191, v120
	v_sub_f32_e32 v120, v126, v125
	v_sub_f32_e32 v141, v141, v125
	v_exp_f32_e32 v126, v120
	v_sub_f32_e32 v120, v123, v125
	v_exp_f32_e32 v141, v141
	v_exp_f32_e32 v125, v120
	v_exp_f32_e32 v124, v127
	s_nop 1
	v_cvt_pk_f16_f32 v122, v190, v191
	v_cvt_pk_f16_f32 v123, v126, v125
	v_cvt_pk_f16_f32 v121, v188, v189
	v_cvt_pk_f16_f32 v120, v141, v183
	v_pk_mul_f32 v[110:111], v[110:111], v[124:125] op_sel_hi:[1,0]
	v_pk_mul_f32 v[108:109], v[108:109], v[124:125] op_sel_hi:[1,0]
	v_pk_mul_f32 v[106:107], v[106:107], v[124:125] op_sel_hi:[1,0]
	v_pk_mul_f32 v[104:105], v[104:105], v[124:125] op_sel_hi:[1,0]
	s_waitcnt lgkmcnt(8)
	v_mfma_f32_16x16x32_f16 v[108:111], v[204:207], v[120:123], v[108:111]
	s_nop 1
	v_pk_mul_f32 v[102:103], v[102:103], v[124:125] op_sel_hi:[1,0]
	v_pk_mul_f32 v[100:101], v[100:101], v[124:125] op_sel_hi:[1,0]
	s_waitcnt lgkmcnt(6)
	v_mfma_f32_16x16x32_f16 v[104:107], v[208:211], v[120:123], v[104:107]
	s_nop 1
	v_pk_mul_f32 v[98:99], v[98:99], v[124:125] op_sel_hi:[1,0]
	v_pk_mul_f32 v[96:97], v[96:97], v[124:125] op_sel_hi:[1,0]
	s_waitcnt lgkmcnt(4)
	v_mfma_f32_16x16x32_f16 v[100:103], v[212:215], v[120:123], v[100:103]
	s_nop 1
	v_pk_mul_f32 v[94:95], v[94:95], v[124:125] op_sel_hi:[1,0]
	v_pk_mul_f32 v[92:93], v[92:93], v[124:125] op_sel_hi:[1,0]
	s_waitcnt lgkmcnt(2)
	v_mfma_f32_16x16x32_f16 v[96:99], v[216:219], v[120:123], v[96:99]
	s_nop 1
	v_pk_mul_f32 v[86:87], v[86:87], v[124:125] op_sel_hi:[1,0]
	v_pk_mul_f32 v[84:85], v[84:85], v[124:125] op_sel_hi:[1,0]
	s_waitcnt lgkmcnt(0)
	v_mfma_f32_16x16x32_f16 v[92:95], v[220:223], v[120:123], v[92:95]
	ds_read_b64_tr_b16 v[184:185], v175
	ds_read_b64_tr_b16 v[186:187], v176
	v_pk_mul_f32 v[74:75], v[74:75], v[124:125] op_sel_hi:[1,0]
	v_pk_mul_f32 v[72:73], v[72:73], v[124:125] op_sel_hi:[1,0]
	s_waitcnt lgkmcnt(0)
	v_mfma_f32_16x16x32_f16 v[84:87], v[184:187], v[120:123], v[84:87]
	ds_read_b64_tr_b16 v[184:185], v177
	ds_read_b64_tr_b16 v[186:187], v178
	v_pk_mul_f32 v[82:83], v[82:83], v[124:125] op_sel_hi:[1,0]
	v_pk_mul_f32 v[80:81], v[80:81], v[124:125] op_sel_hi:[1,0]
	s_waitcnt lgkmcnt(0)
	v_mfma_f32_16x16x32_f16 v[72:75], v[184:187], v[120:123], v[72:75]
	ds_read_b64_tr_b16 v[184:185], v179
	ds_read_b64_tr_b16 v[186:187], v180
	v_cmp_lt_u32_e32 vcc, s6, v139
	s_waitcnt lgkmcnt(0)
	v_mfma_f32_16x16x32_f16 v[80:83], v[184:187], v[120:123], v[80:83]
	v_add_f32_e32 v120, 0, v141
	v_add_f32_e32 v120, v183, v120
	v_add_f32_e32 v120, v188, v120
	v_add_f32_e32 v120, v189, v120
	v_add_f32_e32 v120, v190, v120
	v_add_f32_e32 v120, v191, v120
	v_add_f32_e32 v120, v126, v120
	v_add_f32_e32 v141, v125, v120
	v_fmac_f32_e32 v141, v182, v124
	s_and_saveexec_b64 s[6:7], vcc
	s_cbranch_execz .LBB0_99
	s_branch .Ld5_b103
.Ld5_slow_b:
	v_sub_u32_sdwa v224, v129, v120 dst_sel:DWORD dst_unused:UNUSED_PAD src0_sel:DWORD src1_sel:WORD_0
	v_med3_i32 v224, v224, 0, v233
	v_lshl_add_u32 v224, v224, 2, v148
	ds_read_b32 v224, v224
	v_sub_u32_sdwa v225, v129, v120 dst_sel:DWORD dst_unused:UNUSED_PAD src0_sel:DWORD src1_sel:WORD_1
	v_med3_i32 v225, v225, 0, v233
	v_lshl_add_u32 v225, v225, 2, v148
	ds_read_b32 v225, v225
	v_sub_u32_sdwa v246, v129, v121 dst_sel:DWORD dst_unused:UNUSED_PAD src0_sel:DWORD src1_sel:WORD_0
	v_med3_i32 v246, v246, 0, v233
	v_lshl_add_u32 v246, v246, 2, v148
	ds_read_b32 v246, v246
	v_sub_u32_sdwa v247, v129, v121 dst_sel:DWORD dst_unused:UNUSED_PAD src0_sel:DWORD src1_sel:WORD_1
	v_med3_i32 v247, v247, 0, v233
	v_lshl_add_u32 v247, v247, 2, v148
	ds_read_b32 v247, v247
	v_sub_u32_sdwa v193, v129, v122 dst_sel:DWORD dst_unused:UNUSED_PAD src0_sel:DWORD src1_sel:WORD_0
	v_med3_i32 v193, v193, 0, v233
	v_lshl_add_u32 v193, v193, 2, v148
	ds_read_b32 v193, v193
	v_sub_u32_sdwa v194, v129, v122 dst_sel:DWORD dst_unused:UNUSED_PAD src0_sel:DWORD src1_sel:WORD_1
	v_med3_i32 v194, v194, 0, v233
	v_lshl_add_u32 v194, v194, 2, v148
	ds_read_b32 v194, v194
	v_sub_u32_sdwa v195, v129, v123 dst_sel:DWORD dst_unused:UNUSED_PAD src0_sel:DWORD src1_sel:WORD_0
	v_med3_i32 v195, v195, 0, v233
	v_lshl_add_u32 v195, v195, 2, v148
	ds_read_b32 v195, v195
	v_sub_u32_sdwa v248, v129, v123 dst_sel:DWORD dst_unused:UNUSED_PAD src0_sel:DWORD src1_sel:WORD_1
	v_med3_i32 v248, v248, 0, v233
	v_lshl_add_u32 v248, v248, 2, v148
	ds_read_b32 v248, v248
	ds_read_b128 v[124:127], v157
	ds_read_b128 v[184:187], v158
	ds_read_b128 v[188:191], v162
	s_nop 5
	s_waitcnt lgkmcnt(2)
	v_mfma_f32_16x16x32_f16 v[124:127], v[124:127], v[0:3], 0
	s_nop 0
	v_cmp_ne_u32_sdwa vcc, v120, s59 src0_sel:WORD_0 src1_sel:DWORD
	s_mov_b32 s6, 0xff800000
	s_waitcnt lgkmcnt(1)
	v_mfma_f32_16x16x32_f16 v[124:127], v[184:187], v[4:7], v[124:127]
	ds_read_b128 v[184:187], v159
	s_nop 0
	s_waitcnt lgkmcnt(0)
	v_mfma_f32_16x16x32_f16 v[124:127], v[184:187], v[8:11], v[124:127]
	ds_read_b128 v[184:187], v160
	s_waitcnt lgkmcnt(0)
	v_mfma_f32_16x16x32_f16 v[184:187], v[184:187], v[44:47], v[124:127]
	s_nop 4
	ds_read_b128 v[124:127], v161
	s_nop 1
	v_add_f32_e32 v141, v184, v224
	s_nop 3
	s_waitcnt lgkmcnt(0)
	v_mfma_f32_16x16x32_f16 v[124:127], v[124:127], v[0:3], 0
	v_add_f32_e32 v181, v185, v225
	s_nop 1
	v_mfma_f32_16x16x32_f16 v[124:127], v[188:191], v[4:7], v[124:127]
	ds_read_b128 v[188:191], v163
	s_nop 1
	v_cndmask_b32_e32 v141, v234, v141, vcc
	v_cmp_ne_u32_sdwa vcc, v120, s59 src0_sel:WORD_1 src1_sel:DWORD
	s_waitcnt lgkmcnt(0)
	v_mfma_f32_16x16x32_f16 v[124:127], v[188:191], v[8:11], v[124:127]
	ds_read_b128 v[188:191], v164
	v_cndmask_b32_e32 v120, v234, v181, vcc
	v_add_f32_e32 v184, v186, v246
	v_cmp_ne_u32_sdwa vcc, v121, s59 src0_sel:WORD_0 src1_sel:DWORD
	v_add_f32_e32 v185, v187, v247
	v_max3_f32 v181, v141, s6, v120
	v_cndmask_b32_e32 v184, v234, v184, vcc
	v_cmp_ne_u32_sdwa vcc, v121, s59 src0_sel:WORD_1 src1_sel:DWORD
	s_nop 1
	v_cndmask_b32_e32 v121, v234, v185, vcc
	s_nop 3
	s_waitcnt lgkmcnt(0)
	v_mfma_f32_16x16x32_f16 v[124:127], v[188:191], v[44:47], v[124:127]
	ds_read_b64_tr_b16 v[204:205], v165
	ds_read_b64_tr_b16 v[206:207], v166
	ds_read_b64_tr_b16 v[208:209], v167
	ds_read_b64_tr_b16 v[210:211], v168
	ds_read_b64_tr_b16 v[212:213], v169
	ds_read_b64_tr_b16 v[214:215], v170
	ds_read_b64_tr_b16 v[216:217], v171
	ds_read_b64_tr_b16 v[218:219], v172
	ds_read_b64_tr_b16 v[220:221], v173
	ds_read_b64_tr_b16 v[222:223], v174
	v_cmp_ne_u32_sdwa vcc, v122, s59 src0_sel:WORD_0 src1_sel:DWORD
	v_max3_f32 v181, v181, v184, v121
	s_nop 4
	v_add_f32_e32 v124, v124, v193
	s_nop 3
	v_cndmask_b32_e32 v124, v234, v124, vcc
	v_cmp_ne_u32_sdwa vcc, v122, s59 src0_sel:WORD_1 src1_sel:DWORD
	v_add_f32_e32 v125, v125, v194
	v_cndmask_b32_e32 v122, v234, v125, vcc
	v_max3_f32 v125, v181, v124, v122
	s_nop 3
	v_cmp_ne_u32_sdwa vcc, v123, s59 src0_sel:WORD_0 src1_sel:DWORD
	v_add_f32_e32 v126, v126, v195
	s_nop 3
	v_cndmask_b32_e32 v126, v234, v126, vcc
	v_cmp_ne_u32_sdwa vcc, v123, s59 src0_sel:WORD_1 src1_sel:DWORD
	v_add_f32_e32 v127, v127, v248
	v_cndmask_b32_e32 v123, v234, v127, vcc
	v_max3_f32 v125, v125, v126, v123
	v_mov_b32_e32 v127, v125
	s_nop 1
	v_permlane16_swap_b32_e32 v125, v127
	v_max_f32_e32 v127, v127, v127
	v_max_f32_e32 v125, v125, v125
	v_max_f32_e32 v125, v125, v127
	v_mov_b32_e32 v127, v125
	s_nop 1
	v_permlane32_swap_b32_e32 v125, v127
	v_max3_f32 v181, v183, v125, v127
	v_cmp_neq_f32_e32 vcc, s6, v181
	s_add_i32 s6, s10, -2
	s_nop 0
	v_cndmask_b32_e32 v125, 0, v181, vcc
	v_sub_f32_e32 v120, v120, v125
	v_sub_f32_e32 v127, v183, v125
	v_exp_f32_e32 v183, v120
	v_sub_f32_e32 v120, v184, v125
	v_exp_f32_e32 v188, v120
	v_sub_f32_e32 v120, v121, v125
	v_exp_f32_e32 v189, v120
	v_sub_f32_e32 v120, v124, v125
	v_exp_f32_e32 v190, v120
	v_sub_f32_e32 v120, v122, v125
	v_exp_f32_e32 v191, v120
	v_sub_f32_e32 v120, v126, v125
	v_sub_f32_e32 v141, v141, v125
	v_exp_f32_e32 v126, v120
	v_sub_f32_e32 v120, v123, v125
	v_exp_f32_e32 v141, v141
	v_exp_f32_e32 v125, v120
	v_exp_f32_e32 v124, v127
	s_nop 1
	v_cvt_pk_f16_f32 v122, v190, v191
	v_cvt_pk_f16_f32 v123, v126, v125
	v_cvt_pk_f16_f32 v121, v188, v189
	v_cvt_pk_f16_f32 v120, v141, v183
	v_pk_mul_f32 v[110:111], v[110:111], v[124:125] op_sel_hi:[1,0]
	v_pk_mul_f32 v[108:109], v[108:109], v[124:125] op_sel_hi:[1,0]
	v_pk_mul_f32 v[106:107], v[106:107], v[124:125] op_sel_hi:[1,0]
	v_pk_mul_f32 v[104:105], v[104:105], v[124:125] op_sel_hi:[1,0]
	s_waitcnt lgkmcnt(8)
; #define SA_GATHER(GR, SELV) do { _Pragma("unroll") for (int i = 0; i < 8; ++i) { \
;             unsigned sidx = ((SELV)[i >> 1] >> ((i & 1) * 16)) & 0xFFFFu; sidx = sidx == 0xFFFFu ? 0u : sidx; \
;             (GR)[i] = *(const u32x4*)(kg + (size_t)sidx * 128 + r * 8); } } while (0)
; __device__ __forceinline__ void dsa_attn_phase(const Params& p, int j, unsigned char* smem) {
;     ...
;         SA_GATHER(grA, selA);
;         if (ng > 1) { selB = *(const u32x4*)(srow + 32 + 8 * q); SA_GATHER(grB, selB); }
;         for (int g = 0; g < ng; g += 2) {
;             SA_GROUP(grA, selA, g);
;             if (g + 1 < ng) SA_GROUP(grB, selB, g + 1);
	v_mfma_f32_16x16x32_f16 v[108:111], v[204:207], v[120:123], v[108:111]
	s_nop 1
	v_pk_mul_f32 v[102:103], v[102:103], v[124:125] op_sel_hi:[1,0]
	v_pk_mul_f32 v[100:101], v[100:101], v[124:125] op_sel_hi:[1,0]
	s_waitcnt lgkmcnt(6)
	v_mfma_f32_16x16x32_f16 v[104:107], v[208:211], v[120:123], v[104:107]
	s_nop 1
	v_pk_mul_f32 v[98:99], v[98:99], v[124:125] op_sel_hi:[1,0]
	v_pk_mul_f32 v[96:97], v[96:97], v[124:125] op_sel_hi:[1,0]
	s_waitcnt lgkmcnt(4)
	v_mfma_f32_16x16x32_f16 v[100:103], v[212:215], v[120:123], v[100:103]
	s_nop 1
	v_pk_mul_f32 v[94:95], v[94:95], v[124:125] op_sel_hi:[1,0]
	v_pk_mul_f32 v[92:93], v[92:93], v[124:125] op_sel_hi:[1,0]
	s_waitcnt lgkmcnt(2)
	v_mfma_f32_16x16x32_f16 v[96:99], v[216:219], v[120:123], v[96:99]
	s_nop 1
	v_pk_mul_f32 v[86:87], v[86:87], v[124:125] op_sel_hi:[1,0]
	v_pk_mul_f32 v[84:85], v[84:85], v[124:125] op_sel_hi:[1,0]
	s_waitcnt lgkmcnt(0)
	v_mfma_f32_16x16x32_f16 v[92:95], v[220:223], v[120:123], v[92:95]
	ds_read_b64_tr_b16 v[184:185], v175
	ds_read_b64_tr_b16 v[186:187], v176
	v_pk_mul_f32 v[74:75], v[74:75], v[124:125] op_sel_hi:[1,0]
	v_pk_mul_f32 v[72:73], v[72:73], v[124:125] op_sel_hi:[1,0]
	s_waitcnt lgkmcnt(0)
	v_mfma_f32_16x16x32_f16 v[84:87], v[184:187], v[120:123], v[84:87]
	ds_read_b64_tr_b16 v[184:185], v177
	ds_read_b64_tr_b16 v[186:187], v178
	v_pk_mul_f32 v[82:83], v[82:83], v[124:125] op_sel_hi:[1,0]
	v_pk_mul_f32 v[80:81], v[80:81], v[124:125] op_sel_hi:[1,0]
	s_waitcnt lgkmcnt(0)
	v_mfma_f32_16x16x32_f16 v[72:75], v[184:187], v[120:123], v[72:75]
	ds_read_b64_tr_b16 v[184:185], v179
	ds_read_b64_tr_b16 v[186:187], v180
	v_cmp_lt_u32_e32 vcc, s6, v139
	s_waitcnt lgkmcnt(0)
	v_mfma_f32_16x16x32_f16 v[80:83], v[184:187], v[120:123], v[80:83]
	v_add_f32_e32 v120, 0, v141
	v_add_f32_e32 v120, v183, v120
	v_add_f32_e32 v120, v188, v120
	v_add_f32_e32 v120, v189, v120
	v_add_f32_e32 v120, v190, v120
	v_add_f32_e32 v120, v191, v120
	v_add_f32_e32 v120, v126, v120
	v_add_f32_e32 v141, v125, v120
	v_fmac_f32_e32 v141, v182, v124
	s_and_saveexec_b64 s[6:7], vcc
	s_cbranch_execz .LBB0_99
.Ld5_b103:
	v_mov_b64_e32 v[122:123], v[118:119]
	v_cmp_lt_u32_e32 vcc, s10, v139
	v_mov_b64_e32 v[120:121], v[116:117]
	s_waitcnt vmcnt(0)
	ds_write_b128 v149, v[12:15] offset:8192
	ds_write_b128 v150, v[16:19] offset:8448
	ds_write_b128 v151, v[20:23] offset:8704
	ds_write_b128 v152, v[24:27] offset:8960
	ds_write_b128 v153, v[28:31] offset:8192
	ds_write_b128 v154, v[32:35] offset:8192
	ds_write_b128 v155, v[36:39] offset:8192
	ds_write_b128 v156, v[40:43] offset:8192
	s_and_saveexec_b64 s[8:9], vcc
	s_cbranch_execz .LBB0_98
	ds_read_b128 v[120:123], v238 offset:64
	s_waitcnt lgkmcnt(0)
	v_bfe_u32 v12, v120, 0, 11
	v_bfe_u32 v16, v120, 16, 11
	v_bfe_u32 v20, v121, 0, 11
	v_bfe_u32 v24, v121, 16, 11
	v_bfe_u32 v28, v122, 0, 11
	v_bfe_u32 v32, v122, 16, 11
	v_bfe_u32 v36, v123, 0, 11
	v_bfe_u32 v40, v123, 16, 11
	v_lshl_add_u32 v12, v12, 8, v192
	v_lshl_add_u32 v16, v16, 8, v192
	v_lshl_add_u32 v20, v20, 8, v192
	v_lshl_add_u32 v24, v24, 8, v192
	v_lshl_add_u32 v28, v28, 8, v192
	v_lshl_add_u32 v32, v32, 8, v192
	v_lshl_add_u32 v36, v36, 8, v192
	v_lshl_add_u32 v40, v40, 8, v192
	global_load_dwordx4 v[12:15], v12, s[12:13]
	s_nop 0
	global_load_dwordx4 v[16:19], v16, s[12:13]
	s_nop 0
	global_load_dwordx4 v[20:23], v20, s[12:13]
	s_nop 0
	global_load_dwordx4 v[24:27], v24, s[12:13]
	s_nop 0
	global_load_dwordx4 v[28:31], v28, s[12:13]
	s_nop 0
	global_load_dwordx4 v[32:35], v32, s[12:13]
	s_nop 0
	global_load_dwordx4 v[36:39], v36, s[12:13]
	s_nop 0
	global_load_dwordx4 v[40:43], v40, s[12:13]
	s_branch .LBB0_98
